# v34 plus conv-loop work-item remap: third grid-stride pass spread over lanes 0-31 of every workgroup instead of workgroups 0-15
# speedup vs baseline: 1.0070x; 1.0070x over previous
; __device__ __forceinline__ void ew_phase(const Params& p, int l) {
;     ...
;         const long gt = (long)blockIdx.x * NTHREADS + tid, gn = (long)gridDim.x * NTHREADS;
;         bf16_t* Acat = (bf16_t*)(ws + WS_ACAT);
;         const float* cw = p.in[I_CW] + (size_t)l * 3 * 1024; const float* cbias = p.in[I_CB] + (size_t)l * 1024;
;         for (long it = gt; it < (long)(ROWS / 4) * 128; it += gn) { const int row0 = (int)(it >> 7) * 4, c0 = (int)(it & 127) * 8;
.LBB0_256:
	s_or_b64 exec, exec, s[0:1]
	v_add_u32_e32 v116, -32, v190
	s_mul_i32 s98, s2, 0x1e0
	s_add_i32 s98, s98, 0x2000
	s_lshl_b32 s99, s2, 5
	v_add_u32_e32 v116, s98, v116
	v_add_u32_e32 v117, s99, v190
	v_cmp_gt_u32_e32 vcc, 32, v190
	s_nop 1
	v_cndmask_b32_e32 v114, v116, v117, vcc
	v_mov_b32_e32 v115, 0
	v_lshlrev_b32_e32 v101, 3, v114
	s_mov_b64 s[0:1], 0x42000
	v_cmp_gt_i64_e32 vcc, s[0:1], v[114:115]
	s_and_saveexec_b64 s[0:1], vcc
	s_cbranch_execz .LBB0_265
	s_add_u32 s4, s54, 0x3b828000
	s_addc_u32 s5, s55, 0
	s_mov_b64 s[10:11], 0
	s_branch .LBB0_259
